# chain2: K-loop MFMAs reordered into back-to-back same-accumulator chains (SrcC forwarding), with MFMA-result hazard distances preserved; pure reorder of the six GEMM loops
# speedup vs baseline: 1.0119x; 1.0019x over previous
; #define PG8_STAGE(bufoff, gbase, voff) do { _Pragma("unroll") for (int _i = 0; _i < 2; ++_i) \
;         __builtin_amdgcn_global_load_lds((const unsigned*)((const char*)(gbase) + (voff)[_i]), (LAS unsigned*)(lds + (bufoff) + ldsw + _i * 8192), 16, 0, 0); } while (0)
; #define PG8_LDA(dst, b, h) do { _Pragma("unroll") for (int m = 0; m < 4; ++m) _Pragma("unroll") for (int k = 0; k < 2; ++k) dst[m][k] = *(const LAS bf16x8*)(lds + PG8_SA(b, h) + aoffk[k] + m * 2048); } while (0)
; #define PG8_LDB(dst, b, h) do { _Pragma("unroll") for (int n = 0; n < 2; ++n) _Pragma("unroll") for (int k = 0; k < 2; ++k) dst[n][k] = *(const LAS bf16x8*)(lds + PG8_SB(b, h) + boffk[k] + n * 2048); } while (0)
; #define PG8_WAIT_V(n) asm volatile("s_waitcnt vmcnt(" #n ")" ::: "memory")
; #define PG8_WAIT_L(n) asm volatile("s_waitcnt lgkmcnt(" #n ")" ::: "memory")
; #define PG8_BAR __builtin_amdgcn_s_barrier()
; #define PG8_SCHED __builtin_amdgcn_sched_barrier(0)
; template <class Epi, class Sched, class GemmT>
; __device__ __forceinline__ void gemm_phase(LAS unsigned char* lds, const GemmT& g, const Sched& S, const Epi& E, const int wid) {
;     ...
;             const int nt = cs.nt;
;             for (int t = 0; t < nt; t += 2) {
;                 const bool last = (t == nt - 2);
;                 const char* a1 = cA + (size_t)(t + 1) * kstep;
;                 const char* a2 = last ? ns.A : cA + (size_t)(t + 2) * kstep; const char* b2 = last ? ns.B : cB + (size_t)(t + 2) * kstep;
;                 const char* a3 = a2 + kstep; const char* b3 = b2 + kstep;
;                 unsigned vA2[2], vB2[2];
; #pragma unroll
;                 for (int i = 0; i < 2; ++i) { vA2[i] = last ? nvA[i] : voffA[i]; vB2[i] = last ? nvB[i] : voffB[i]; }
;                 const size_t hA2 = last ? nhA : hstepA, hB2 = last ? nhB : hstepB;
;                 PG8_LDB(B0, 0, 0); PG8_LDB(B1, 0, 1); PG8_SCHED; PG8_LDA(At, 0, 0); PG8_STAGE(PG8_SA(1, 1), a1 + hstepA, voffA);
;                 PG8_WAIT_V(8); PG8_WAIT_L(0); PG8_BAR; PG8_MMA(0, 0, At, B0); PG8_MMA(0, 1, At, B1); PG8_BAR; PG8_SCHED;
;                 PG8_LDA(At, 0, 1); PG8_STAGE(PG8_SB(0, 0), b2, vB2); PG8_STAGE(PG8_SB(0, 1), b2 + hB2, vB2); PG8_STAGE(PG8_SA(0, 0), a2, vA2);
;                 PG8_WAIT_V(8); PG8_WAIT_L(0); PG8_BAR; PG8_MMA(1, 0, At, B0); PG8_MMA(1, 1, At, B1); PG8_BAR; PG8_SCHED;
.LBB0_936:
	ds_read_b128 v[12:15], v223
	ds_read_b128 v[132:135], v224
	ds_read_b128 v[136:139], v225
	ds_read_b128 v[140:143], v226
	ds_read_b128 v[144:147], v227
	ds_read_b128 v[148:151], v229
	ds_read_b128 v[152:155], v230
	ds_read_b128 v[156:159], v231
	s_add_u32 s66, s64, 0xfff00080
	s_addc_u32 s67, s65, -1
	s_cmp_eq_u32 s81, 60
	s_cselect_b32 s71, s57, s67
	s_cselect_b32 s70, s56, s66
	s_cselect_b32 s67, s77, s79
	s_cselect_b32 s66, s63, s78
	v_lshl_add_u64 v[204:205], s[64:65], 0, v[176:177]
	s_add_i32 m0, s14, 0xc000
	ds_read_b128 v[160:163], v232
	ds_read_b128 v[164:167], v232 offset:2048
	ds_read_b128 v[168:171], v233
	ds_read_b128 v[172:175], v233 offset:2048
	ds_read_b128 v[188:191], v232 offset:4096
	ds_read_b128 v[192:195], v232 offset:6144
	ds_read_b128 v[196:199], v233 offset:4096
	ds_read_b128 v[200:203], v233 offset:6144
	global_load_lds_dwordx4 v[204:205], off
	v_lshl_add_u64 v[204:205], s[64:65], 0, v[180:181]
	s_add_i32 m0, s14, 0xe000
	s_nop 0
	global_load_lds_dwordx4 v[204:205], off
	s_waitcnt vmcnt(8)
	s_waitcnt lgkmcnt(0)
	s_barrier
	s_setprio 3
	s_waitcnt lgkmcnt(0)
	v_mfma_f32_16x16x32_bf16 v[124:127], v[12:15], v[160:163], v[124:127]
	v_mfma_f32_16x16x32_bf16 v[124:127], v[132:135], v[168:171], v[124:127]
	v_mfma_f32_16x16x32_bf16 v[120:123], v[136:139], v[160:163], v[120:123]
	v_mfma_f32_16x16x32_bf16 v[120:123], v[140:143], v[168:171], v[120:123]
	v_mfma_f32_16x16x32_bf16 v[40:43], v[12:15], v[164:167], v[40:43]
	v_mfma_f32_16x16x32_bf16 v[40:43], v[132:135], v[172:175], v[40:43]
	v_mfma_f32_16x16x32_bf16 v[104:107], v[136:139], v[164:167], v[104:107]
	v_mfma_f32_16x16x32_bf16 v[104:107], v[140:143], v[172:175], v[104:107]
	v_mfma_f32_16x16x32_bf16 v[32:35], v[12:15], v[188:191], v[32:35]
	v_mfma_f32_16x16x32_bf16 v[32:35], v[132:135], v[196:199], v[32:35]
	v_mfma_f32_16x16x32_bf16 v[96:99], v[136:139], v[188:191], v[96:99]
	v_mfma_f32_16x16x32_bf16 v[96:99], v[140:143], v[196:199], v[96:99]
	v_mfma_f32_16x16x32_bf16 v[112:115], v[12:15], v[192:195], v[112:115]
	v_mfma_f32_16x16x32_bf16 v[112:115], v[132:135], v[200:203], v[112:115]
	v_mfma_f32_16x16x32_bf16 v[92:95], v[136:139], v[192:195], v[92:95]
	v_mfma_f32_16x16x32_bf16 v[92:95], v[140:143], v[200:203], v[92:95]
	s_setprio 0
	s_setprio 3
	v_mfma_f32_16x16x32_bf16 v[68:71], v[144:147], v[160:163], v[68:71]
	v_mfma_f32_16x16x32_bf16 v[68:71], v[148:151], v[168:171], v[68:71]
	v_mfma_f32_16x16x32_bf16 v[60:63], v[152:155], v[160:163], v[60:63]
	v_mfma_f32_16x16x32_bf16 v[60:63], v[156:159], v[168:171], v[60:63]
	v_mfma_f32_16x16x32_bf16 v[76:79], v[144:147], v[164:167], v[76:79]
	v_mfma_f32_16x16x32_bf16 v[76:79], v[148:151], v[172:175], v[76:79]
	v_mfma_f32_16x16x32_bf16 v[20:23], v[152:155], v[164:167], v[20:23]
	v_mfma_f32_16x16x32_bf16 v[20:23], v[156:159], v[172:175], v[20:23]
	v_mfma_f32_16x16x32_bf16 v[72:75], v[144:147], v[188:191], v[72:75]
	v_mfma_f32_16x16x32_bf16 v[72:75], v[148:151], v[196:199], v[72:75]
	v_mfma_f32_16x16x32_bf16 v[16:19], v[152:155], v[188:191], v[16:19]
	v_mfma_f32_16x16x32_bf16 v[16:19], v[156:159], v[196:199], v[16:19]
	v_mfma_f32_16x16x32_bf16 v[84:87], v[144:147], v[192:195], v[84:87]
	v_mfma_f32_16x16x32_bf16 v[84:87], v[148:151], v[200:203], v[84:87]
	v_mfma_f32_16x16x32_bf16 v[80:83], v[152:155], v[192:195], v[80:83]
	v_mfma_f32_16x16x32_bf16 v[80:83], v[156:159], v[200:203], v[80:83]
	s_setprio 0
	s_barrier
	s_add_i32 s80, s69, s68
	v_lshl_add_u64 v[204:205], s[66:67], 0, v[178:179]
	s_mov_b32 m0, s80
	ds_read_b128 v[160:163], v232 offset:16384
	ds_read_b128 v[164:167], v232 offset:18432
	ds_read_b128 v[168:171], v233 offset:16384
	ds_read_b128 v[172:175], v233 offset:18432
	ds_read_b128 v[188:191], v232 offset:20480
	ds_read_b128 v[192:195], v232 offset:22528
	ds_read_b128 v[196:199], v233 offset:20480
	ds_read_b128 v[200:203], v233 offset:22528
	global_load_lds_dwordx4 v[204:205], off
	s_add_i32 m0, s80, 0x2000
	s_add_u32 s82, s66, 0x100000
	v_lshl_add_u64 v[206:207], s[66:67], 0, v[182:183]
	s_addc_u32 s83, s67, 0
	s_add_i32 s80, s72, s68
	global_load_lds_dwordx4 v[206:207], off
	v_lshl_add_u64 v[240:241], s[82:83], 0, v[178:179]
	s_mov_b32 m0, s80
	v_lshl_add_u64 v[242:243], s[70:71], 0, v[180:181]
	global_load_lds_dwordx4 v[240:241], off
	v_lshl_add_u64 v[240:241], s[82:83], 0, v[182:183]
	s_add_i32 m0, s80, 0x2000
	s_nop 0
	global_load_lds_dwordx4 v[240:241], off
	v_lshl_add_u64 v[240:241], s[70:71], 0, v[176:177]
	s_mov_b32 m0, s14
	s_nop 0
	global_load_lds_dwordx4 v[240:241], off
	s_mov_b32 m0, s15
	s_nop 0
	global_load_lds_dwordx4 v[242:243], off
	s_waitcnt vmcnt(8)
	s_waitcnt lgkmcnt(0)
	s_barrier
; #define PG8_STAGE(bufoff, gbase, voff) do { _Pragma("unroll") for (int _i = 0; _i < 2; ++_i) \
;         __builtin_amdgcn_global_load_lds((const unsigned*)((const char*)(gbase) + (voff)[_i]), (LAS unsigned*)(lds + (bufoff) + ldsw + _i * 8192), 16, 0, 0); } while (0)
; #define PG8_LDA(dst, b, h) do { _Pragma("unroll") for (int m = 0; m < 4; ++m) _Pragma("unroll") for (int k = 0; k < 2; ++k) dst[m][k] = *(const LAS bf16x8*)(lds + PG8_SA(b, h) + aoffk[k] + m * 2048); } while (0)
; #define PG8_LDB(dst, b, h) do { _Pragma("unroll") for (int n = 0; n < 2; ++n) _Pragma("unroll") for (int k = 0; k < 2; ++k) dst[n][k] = *(const LAS bf16x8*)(lds + PG8_SB(b, h) + boffk[k] + n * 2048); } while (0)
; #define PG8_WAIT_V(n) asm volatile("s_waitcnt vmcnt(" #n ")" ::: "memory")
; #define PG8_WAIT_L(n) asm volatile("s_waitcnt lgkmcnt(" #n ")" ::: "memory")
; #define PG8_BAR __builtin_amdgcn_s_barrier()
; #define PG8_SCHED __builtin_amdgcn_sched_barrier(0)
; template <class Epi, class Sched, class GemmT>
; __device__ __forceinline__ void gemm_phase(LAS unsigned char* lds, const GemmT& g, const Sched& S, const Epi& E, const int wid) {
;     ...
;                 PG8_WAIT_V(8); PG8_WAIT_L(0); PG8_BAR; PG8_MMA(0, 0, At, B0); PG8_MMA(0, 1, At, B1); PG8_BAR; PG8_SCHED;
;                 PG8_LDA(At, 0, 1); PG8_STAGE(PG8_SB(0, 0), b2, vB2); PG8_STAGE(PG8_SB(0, 1), b2 + hB2, vB2); PG8_STAGE(PG8_SA(0, 0), a2, vA2);
;                 PG8_WAIT_V(8); PG8_WAIT_L(0); PG8_BAR; PG8_MMA(1, 0, At, B0); PG8_MMA(1, 1, At, B1); PG8_BAR; PG8_SCHED;
;                 PG8_LDB(B0, 1, 0); PG8_LDB(B1, 1, 1); PG8_SCHED; PG8_LDA(At, 1, 0); PG8_STAGE(PG8_SA(0, 1), a2 + hA2, vA2);
;                 PG8_WAIT_V(8); PG8_WAIT_L(0); PG8_BAR; PG8_MMA(0, 0, At, B0); PG8_MMA(0, 1, At, B1); PG8_BAR; PG8_SCHED;
	s_setprio 3
	s_waitcnt lgkmcnt(0)
	v_mfma_f32_16x16x32_bf16 v[56:59], v[12:15], v[160:163], v[56:59]
	v_mfma_f32_16x16x32_bf16 v[56:59], v[132:135], v[168:171], v[56:59]
	v_mfma_f32_16x16x32_bf16 v[108:111], v[136:139], v[160:163], v[108:111]
	v_mfma_f32_16x16x32_bf16 v[108:111], v[140:143], v[168:171], v[108:111]
	v_mfma_f32_16x16x32_bf16 v[36:39], v[12:15], v[164:167], v[36:39]
	v_mfma_f32_16x16x32_bf16 v[36:39], v[132:135], v[172:175], v[36:39]
	v_mfma_f32_16x16x32_bf16 v[100:103], v[136:139], v[164:167], v[100:103]
	v_mfma_f32_16x16x32_bf16 v[100:103], v[140:143], v[172:175], v[100:103]
	v_mfma_f32_16x16x32_bf16 v[28:31], v[12:15], v[188:191], v[28:31]
	v_mfma_f32_16x16x32_bf16 v[28:31], v[132:135], v[196:199], v[28:31]
	v_mfma_f32_16x16x32_bf16 v[88:91], v[136:139], v[188:191], v[88:91]
	v_mfma_f32_16x16x32_bf16 v[88:91], v[140:143], v[196:199], v[88:91]
	v_mfma_f32_16x16x32_bf16 v[24:27], v[136:139], v[192:195], v[24:27]
	v_mfma_f32_16x16x32_bf16 v[24:27], v[140:143], v[200:203], v[24:27]
	v_mfma_f32_16x16x32_bf16 v[12:15], v[12:15], v[192:195], v[64:67]
	v_mfma_f32_16x16x32_bf16 v[12:15], v[132:135], v[200:203], v[12:15]
	s_setprio 0
	s_setprio 3
	v_mfma_f32_16x16x32_bf16 v[64:67], v[144:147], v[192:195], v[116:119]
	v_mfma_f32_16x16x32_bf16 v[116:119], v[148:151], v[200:203], v[64:67]
	v_mfma_f32_16x16x32_bf16 v[44:47], v[144:147], v[160:163], v[44:47]
	v_mfma_f32_16x16x32_bf16 v[44:47], v[148:151], v[168:171], v[44:47]
	v_mfma_f32_16x16x32_bf16 v[0:3], v[152:155], v[160:163], v[0:3]
	v_mfma_f32_16x16x32_bf16 v[0:3], v[156:159], v[168:171], v[0:3]
	v_mfma_f32_16x16x32_bf16 v[48:51], v[144:147], v[164:167], v[48:51]
	v_mfma_f32_16x16x32_bf16 v[48:51], v[148:151], v[172:175], v[48:51]
	v_mfma_f32_16x16x32_bf16 v[4:7], v[152:155], v[164:167], v[4:7]
	v_mfma_f32_16x16x32_bf16 v[4:7], v[156:159], v[172:175], v[4:7]
	v_mfma_f32_16x16x32_bf16 v[64:67], v[152:155], v[192:195], v[128:131]
	v_mfma_f32_16x16x32_bf16 v[128:131], v[156:159], v[200:203], v[64:67]
	v_mfma_f32_16x16x32_bf16 v[52:55], v[144:147], v[188:191], v[52:55]
	v_mfma_f32_16x16x32_bf16 v[52:55], v[148:151], v[196:199], v[52:55]
	v_mfma_f32_16x16x32_bf16 v[8:11], v[152:155], v[188:191], v[8:11]
	v_mfma_f32_16x16x32_bf16 v[8:11], v[156:159], v[196:199], v[8:11]
	s_setprio 0
	s_barrier
	s_add_i32 s80, 0, 0x18000
	s_add_i32 s82, 0, 0x1c000
	v_add_u32_e32 v64, s80, v210
	v_add_u32_e32 v132, s80, v211
	v_add_u32_e32 v144, s82, v210
	v_add_u32_e32 v148, s82, v211
	ds_read_b128 v[64:67], v64
	ds_read_b128 v[132:135], v132
	ds_read_b128 v[136:139], v234
	ds_read_b128 v[140:143], v235
	ds_read_b128 v[144:147], v144
	ds_read_b128 v[148:151], v148
	ds_read_b128 v[152:155], v236
	ds_read_b128 v[156:159], v237
	s_add_u32 s70, s70, 0x100000
	s_addc_u32 s71, s71, 0
	s_mov_b32 m0, s23
	v_lshl_add_u64 v[244:245], s[70:71], 0, v[176:177]
	ds_read_b128 v[160:163], v232 offset:32768
	ds_read_b128 v[164:167], v232 offset:34816
	ds_read_b128 v[168:171], v233 offset:32768
	ds_read_b128 v[172:175], v233 offset:34816
	ds_read_b128 v[188:191], v232 offset:36864
	ds_read_b128 v[192:195], v232 offset:38912
	ds_read_b128 v[196:199], v233 offset:36864
	ds_read_b128 v[200:203], v233 offset:38912
	global_load_lds_dwordx4 v[244:245], off
	v_lshl_add_u64 v[244:245], s[70:71], 0, v[180:181]
	s_mov_b32 m0, s34
	s_nop 0
	global_load_lds_dwordx4 v[244:245], off
	s_waitcnt vmcnt(8)
	s_waitcnt lgkmcnt(0)
	s_barrier
	s_setprio 3
	s_waitcnt lgkmcnt(0)
	v_mfma_f32_16x16x32_bf16 v[124:127], v[64:67], v[160:163], v[124:127]
	v_mfma_f32_16x16x32_bf16 v[124:127], v[132:135], v[168:171], v[124:127]
	v_mfma_f32_16x16x32_bf16 v[120:123], v[136:139], v[160:163], v[120:123]
	v_mfma_f32_16x16x32_bf16 v[120:123], v[140:143], v[168:171], v[120:123]
	v_mfma_f32_16x16x32_bf16 v[40:43], v[64:67], v[164:167], v[40:43]
	v_mfma_f32_16x16x32_bf16 v[40:43], v[132:135], v[172:175], v[40:43]
	v_mfma_f32_16x16x32_bf16 v[104:107], v[136:139], v[164:167], v[104:107]
	v_mfma_f32_16x16x32_bf16 v[104:107], v[140:143], v[172:175], v[104:107]
	v_mfma_f32_16x16x32_bf16 v[32:35], v[64:67], v[188:191], v[32:35]
	v_mfma_f32_16x16x32_bf16 v[32:35], v[132:135], v[196:199], v[32:35]
	v_mfma_f32_16x16x32_bf16 v[96:99], v[136:139], v[188:191], v[96:99]
	v_mfma_f32_16x16x32_bf16 v[96:99], v[140:143], v[196:199], v[96:99]
	v_mfma_f32_16x16x32_bf16 v[112:115], v[64:67], v[192:195], v[112:115]
	v_mfma_f32_16x16x32_bf16 v[112:115], v[132:135], v[200:203], v[112:115]
	v_mfma_f32_16x16x32_bf16 v[92:95], v[136:139], v[192:195], v[92:95]
	v_mfma_f32_16x16x32_bf16 v[92:95], v[140:143], v[200:203], v[92:95]
	s_setprio 0
	s_setprio 3
	v_mfma_f32_16x16x32_bf16 v[68:71], v[144:147], v[160:163], v[68:71]
	v_mfma_f32_16x16x32_bf16 v[68:71], v[148:151], v[168:171], v[68:71]
	v_mfma_f32_16x16x32_bf16 v[60:63], v[152:155], v[160:163], v[60:63]
	v_mfma_f32_16x16x32_bf16 v[60:63], v[156:159], v[168:171], v[60:63]
	v_mfma_f32_16x16x32_bf16 v[76:79], v[144:147], v[164:167], v[76:79]
	v_mfma_f32_16x16x32_bf16 v[76:79], v[148:151], v[172:175], v[76:79]
	v_mfma_f32_16x16x32_bf16 v[20:23], v[152:155], v[164:167], v[20:23]
	v_mfma_f32_16x16x32_bf16 v[20:23], v[156:159], v[172:175], v[20:23]
	v_mfma_f32_16x16x32_bf16 v[72:75], v[144:147], v[188:191], v[72:75]
	v_mfma_f32_16x16x32_bf16 v[72:75], v[148:151], v[196:199], v[72:75]
	v_mfma_f32_16x16x32_bf16 v[16:19], v[152:155], v[188:191], v[16:19]
	v_mfma_f32_16x16x32_bf16 v[16:19], v[156:159], v[196:199], v[16:19]
	v_mfma_f32_16x16x32_bf16 v[84:87], v[144:147], v[192:195], v[84:87]
	v_mfma_f32_16x16x32_bf16 v[84:87], v[148:151], v[200:203], v[84:87]
	v_mfma_f32_16x16x32_bf16 v[80:83], v[152:155], v[192:195], v[80:83]
	v_mfma_f32_16x16x32_bf16 v[80:83], v[156:159], v[200:203], v[80:83]
	s_setprio 0
	s_barrier
; #define PG8_STAGE(bufoff, gbase, voff) do { _Pragma("unroll") for (int _i = 0; _i < 2; ++_i) \
;         __builtin_amdgcn_global_load_lds((const unsigned*)((const char*)(gbase) + (voff)[_i]), (LAS unsigned*)(lds + (bufoff) + ldsw + _i * 8192), 16, 0, 0); } while (0)
; #define PG8_LDA(dst, b, h) do { _Pragma("unroll") for (int m = 0; m < 4; ++m) _Pragma("unroll") for (int k = 0; k < 2; ++k) dst[m][k] = *(const LAS bf16x8*)(lds + PG8_SA(b, h) + aoffk[k] + m * 2048); } while (0)
; #define PG8_WAIT_V(n) asm volatile("s_waitcnt vmcnt(" #n ")" ::: "memory")
; #define PG8_WAIT_L(n) asm volatile("s_waitcnt lgkmcnt(" #n ")" ::: "memory")
; #define PG8_BAR __builtin_amdgcn_s_barrier()
; #define PG8_SCHED __builtin_amdgcn_sched_barrier(0)
; template <class Epi, class Sched, class GemmT>
; __device__ __forceinline__ void gemm_phase(LAS unsigned char* lds, const GemmT& g, const Sched& S, const Epi& E, const int wid) {
;     ...
;                 PG8_LDA(At, 1, 1); PG8_STAGE(PG8_SB(1, 0), b3, vB2); PG8_STAGE(PG8_SB(1, 1), b3 + hB2, vB2); PG8_STAGE(PG8_SA(1, 0), a3, vA2);
;                 PG8_WAIT_V(8); PG8_WAIT_L(0); PG8_BAR; PG8_MMA(1, 0, At, B0); PG8_MMA(1, 1, At, B1); PG8_BAR; PG8_SCHED;
	s_add_i32 s70, s80, s68
	v_lshl_add_u64 v[204:205], v[204:205], 0, s[38:39]
	s_mov_b32 m0, s70
	ds_read_b128 v[160:163], v232 offset:49152
	ds_read_b128 v[164:167], v232 offset:51200
	ds_read_b128 v[168:171], v233 offset:49152
	ds_read_b128 v[172:175], v233 offset:51200
	ds_read_b128 v[188:191], v232 offset:53248
	ds_read_b128 v[192:195], v232 offset:55296
	ds_read_b128 v[196:199], v233 offset:53248
	ds_read_b128 v[200:203], v233 offset:55296
	global_load_lds_dwordx4 v[204:205], off
	s_add_i32 m0, s70, 0x2000
	s_add_u32 s66, s66, 0x100080
	v_lshl_add_u64 v[204:205], v[206:207], 0, s[38:39]
	s_addc_u32 s67, s67, 0
	s_add_i32 s70, s82, s68
	global_load_lds_dwordx4 v[204:205], off
	v_lshl_add_u64 v[204:205], s[66:67], 0, v[178:179]
	s_mov_b32 m0, s70
	s_nop 0
	global_load_lds_dwordx4 v[204:205], off
	v_lshl_add_u64 v[204:205], s[66:67], 0, v[182:183]
	s_add_i32 m0, s70, 0x2000
	s_nop 0
	global_load_lds_dwordx4 v[204:205], off
	v_lshl_add_u64 v[204:205], v[240:241], 0, s[38:39]
	s_mov_b32 m0, s54
	s_nop 0
	global_load_lds_dwordx4 v[204:205], off
	v_lshl_add_u64 v[204:205], v[242:243], 0, s[38:39]
	s_mov_b32 m0, s55
	s_nop 0
	global_load_lds_dwordx4 v[204:205], off
	s_waitcnt vmcnt(8)
	s_waitcnt lgkmcnt(0)
	s_barrier
	s_setprio 3
	s_waitcnt lgkmcnt(0)
	v_mfma_f32_16x16x32_bf16 v[12:15], v[64:67], v[192:195], v[12:15]
	v_mfma_f32_16x16x32_bf16 v[56:59], v[64:67], v[160:163], v[56:59]
	v_mfma_f32_16x16x32_bf16 v[56:59], v[132:135], v[168:171], v[56:59]
	v_mfma_f32_16x16x32_bf16 v[108:111], v[136:139], v[160:163], v[108:111]
	v_mfma_f32_16x16x32_bf16 v[108:111], v[140:143], v[168:171], v[108:111]
	v_mfma_f32_16x16x32_bf16 v[36:39], v[64:67], v[164:167], v[36:39]
	v_mfma_f32_16x16x32_bf16 v[36:39], v[132:135], v[172:175], v[36:39]
	v_mfma_f32_16x16x32_bf16 v[100:103], v[136:139], v[164:167], v[100:103]
	v_mfma_f32_16x16x32_bf16 v[100:103], v[140:143], v[172:175], v[100:103]
	v_mfma_f32_16x16x32_bf16 v[28:31], v[64:67], v[188:191], v[28:31]
	v_mfma_f32_16x16x32_bf16 v[28:31], v[132:135], v[196:199], v[28:31]
	v_mfma_f32_16x16x32_bf16 v[88:91], v[136:139], v[188:191], v[88:91]
	v_mfma_f32_16x16x32_bf16 v[88:91], v[140:143], v[196:199], v[88:91]
	v_mfma_f32_16x16x32_bf16 v[64:67], v[132:135], v[200:203], v[12:15]
	v_mfma_f32_16x16x32_bf16 v[12:15], v[136:139], v[192:195], v[24:27]
	v_mfma_f32_16x16x32_bf16 v[24:27], v[140:143], v[200:203], v[12:15]
	s_setprio 0
	s_setprio 3
	v_mfma_f32_16x16x32_bf16 v[12:15], v[144:147], v[160:163], v[44:47]
	v_mfma_f32_16x16x32_bf16 v[44:47], v[148:151], v[168:171], v[12:15]
	v_mfma_f32_16x16x32_bf16 v[0:3], v[152:155], v[160:163], v[0:3]
	v_mfma_f32_16x16x32_bf16 v[0:3], v[156:159], v[168:171], v[0:3]
	v_mfma_f32_16x16x32_bf16 v[4:7], v[152:155], v[164:167], v[4:7]
	v_mfma_f32_16x16x32_bf16 v[4:7], v[156:159], v[172:175], v[4:7]
	v_mfma_f32_16x16x32_bf16 v[12:15], v[144:147], v[164:167], v[48:51]
	v_mfma_f32_16x16x32_bf16 v[48:51], v[148:151], v[172:175], v[12:15]
	v_mfma_f32_16x16x32_bf16 v[8:11], v[152:155], v[188:191], v[8:11]
	v_mfma_f32_16x16x32_bf16 v[8:11], v[156:159], v[196:199], v[8:11]
	v_mfma_f32_16x16x32_bf16 v[12:15], v[144:147], v[188:191], v[52:55]
	v_mfma_f32_16x16x32_bf16 v[52:55], v[148:151], v[196:199], v[12:15]
	v_mfma_f32_16x16x32_bf16 v[12:15], v[144:147], v[192:195], v[116:119]
	v_mfma_f32_16x16x32_bf16 v[116:119], v[148:151], v[200:203], v[12:15]
	v_mfma_f32_16x16x32_bf16 v[12:15], v[152:155], v[192:195], v[128:131]
	v_mfma_f32_16x16x32_bf16 v[128:131], v[156:159], v[200:203], v[12:15]
	s_setprio 0
	s_barrier
	s_add_i32 s81, s81, 2
	s_add_u32 s64, s64, 0x100
	s_addc_u32 s65, s65, 0
	s_add_u32 s78, s78, 0x100
	s_addc_u32 s79, s79, 0
	s_cmp_gt_u32 s81, 61
	s_cbranch_scc0 .LBB0_936
	s_and_b64 vcc, exec, s[40:41]
	s_cbranch_vccz .LBB0_939
	s_barrier
